# final phase: x loads without nt hint as well
# speedup vs baseline: 1.0042x; 1.0042x over previous
; DI float bflo(unsigned w) { return __uint_as_float(w << 16); }
; DI float bfhi(unsigned w) { return __uint_as_float(w & 0xffff0000u); }
; DI void phase_final(const Params& p) {
;     ...
;     for (int row = (blockIdx.x * 8 + wid) * 2; row < S; row += gridDim.x * 16) {
;         f32x4 xv[2][8]; u32x2 yv[2][8]; float sq[2];
; #pragma unroll
;         for (int r = 0; r < 2; ++r) {
;             sq[r] = lane < 32 ? ssq[(size_t)(row + r) * 32 + lane] : 0.f;
; #pragma unroll
;             for (int i = 0; i < 8; ++i) { const size_t off = (size_t)(row + r) * DM + i * 256 + lane * 4; xv[r][i] = __builtin_nontemporal_load((const f32x4*)(x + off)); yv[r][i] = __builtin_nontemporal_load((const u32x2*)(o2 + off)); }
;         }
; #pragma unroll
;         for (int r = 0; r < 2; ++r) {
;             const float rs = rsqrtf(wave_sum(sq[r]) * (1.f / DM) + EPS);
; #pragma unroll
;             for (int i = 0; i < 8; ++i) { const size_t off = (size_t)(row + r) * DM + i * 256 + lane * 4;
;                 const f32x4 ov = {xv[r][i][0] + bflo(yv[r][i][0]) * rs * w[i][0], xv[r][i][1] + bfhi(yv[r][i][0]) * rs * w[i][1],
;                                   xv[r][i][2] + bflo(yv[r][i][1]) * rs * w[i][2], xv[r][i][3] + bfhi(yv[r][i][1]) * rs * w[i][3]};
;                 __builtin_nontemporal_store(ov, (f32x4*)(p.out + off)); }
;         }
.LBB0_598:
	s_or_b64 exec, exec, s[0:1]
	v_lshlrev_b64 v[108:109], 11, v[118:119]
	v_or_b32_e32 v108, v108, v100
	v_lshlrev_b64 v[34:35], 1, v[108:109]
	v_lshl_add_u64 v[32:33], v[108:109], 2, s[2:3]
	v_lshl_add_u64 v[36:37], s[4:5], 0, v[34:35]
	v_or_b32_e32 v38, 0x200, v34
	v_mov_b32_e32 v39, v35
	v_or_b32_e32 v40, 0x400, v34
	v_mov_b32_e32 v41, v35
	v_or_b32_e32 v34, 0x600, v34
	global_load_dwordx4 v[68:71], v[32:33], off
	global_load_dwordx4 v[56:59], v[32:33], off offset:1024
	v_lshl_add_u64 v[38:39], s[4:5], 0, v[38:39]
	v_lshl_add_u64 v[40:41], s[4:5], 0, v[40:41]
	global_load_dwordx4 v[52:55], v[32:33], off offset:2048
	global_load_dwordx4 v[48:51], v[32:33], off offset:3072
	v_lshl_add_u64 v[32:33], s[4:5], 0, v[34:35]
	global_load_dwordx2 v[124:125], v[36:37], off
	global_load_dwordx2 v[122:123], v[38:39], off
	global_load_dwordx2 v[120:121], v[40:41], off
	global_load_dwordx2 v[116:117], v[32:33], off
	s_waitcnt vmcnt(0)
	ds_bpermute_b32 v149, v101, v127
	ds_bpermute_b32 v148, v101, v126
	v_or_b32_e32 v32, 0x400, v108
	v_mov_b32_e32 v33, v109
	v_lshl_add_u64 v[34:35], v[32:33], 2, s[2:3]
	v_lshl_add_u64 v[32:33], v[32:33], 1, s[4:5]
	s_waitcnt lgkmcnt(0)
	v_pk_add_f32 v[126:127], v[126:127], v[148:149]
	ds_bpermute_b32 v149, v107, v127
	ds_bpermute_b32 v148, v107, v126
	global_load_dwordx2 v[114:115], v[32:33], off
	global_load_dwordx4 v[44:47], v[34:35], off
	v_or_b32_e32 v32, 0x500, v108
	v_mov_b32_e32 v33, v109
	s_waitcnt lgkmcnt(0)
	v_pk_add_f32 v[126:127], v[126:127], v[148:149]
	ds_bpermute_b32 v149, v144, v127
	ds_bpermute_b32 v148, v144, v126
	v_lshl_add_u64 v[34:35], v[32:33], 2, s[2:3]
	v_lshl_add_u64 v[32:33], v[32:33], 1, s[4:5]
	global_load_dwordx2 v[112:113], v[32:33], off
	global_load_dwordx4 v[40:43], v[34:35], off
	v_or_b32_e32 v32, 0x600, v108
	v_mov_b32_e32 v33, v109
	s_waitcnt lgkmcnt(0)
	v_pk_add_f32 v[126:127], v[126:127], v[148:149]
	v_lshl_add_u64 v[34:35], v[32:33], 2, s[2:3]
	v_lshl_add_u64 v[32:33], v[32:33], 1, s[4:5]
	ds_bpermute_b32 v149, v145, v127
	ds_bpermute_b32 v148, v145, v126
	global_load_dwordx2 v[110:111], v[32:33], off
	global_load_dwordx4 v[36:39], v[34:35], off
	v_or_b32_e32 v108, 0x700, v108
	v_lshl_add_u64 v[32:33], v[108:109], 2, s[2:3]
	v_lshl_add_u64 v[108:109], v[108:109], 1, s[4:5]
	s_waitcnt lgkmcnt(0)
	v_pk_add_f32 v[126:127], v[126:127], v[148:149]
	global_load_dwordx2 v[108:109], v[108:109], off
	ds_bpermute_b32 v149, v146, v127
	ds_bpermute_b32 v148, v146, v126
	global_load_dwordx4 v[32:35], v[32:33], off
	v_lshlrev_b64 v[150:151], 13, v[96:97]
	v_lshlrev_b32_e32 v152, 16, v142
	v_and_b32_e32 v153, 0xffff0000, v142
	s_waitcnt lgkmcnt(0)
	v_pk_add_f32 v[126:127], v[126:127], v[148:149]
	ds_bpermute_b32 v149, v147, v127
	ds_bpermute_b32 v148, v147, v126
	v_lshlrev_b32_e32 v142, 16, v143
	v_and_b32_e32 v143, 0xffff0000, v143
	v_lshl_add_u64 v[154:155], v[104:105], 0, v[150:151]
	v_lshlrev_b32_e32 v156, 16, v140
	s_waitcnt lgkmcnt(0)
	v_pk_add_f32 v[126:127], v[126:127], v[148:149]
	v_and_b32_e32 v157, 0xffff0000, v140
	v_pk_fma_f32 v[126:127], v[126:127], s[10:11], v[106:107] op_sel_hi:[1,0,0]
	v_lshlrev_b32_e32 v140, 16, v141
	v_mul_f32_e32 v97, 0x4b800000, v127
	v_cmp_gt_f32_e64 s[0:1], s13, v127
	v_and_b32_e32 v141, 0xffff0000, v141
	v_lshl_add_u64 v[150:151], s[6:7], 0, v[150:151]
	v_cndmask_b32_e64 v97, v127, v97, s[0:1]
	v_rsq_f32_e32 v97, v97
	v_lshlrev_b32_e32 v98, 2, v100
	v_lshl_add_u64 v[150:151], v[150:151], 0, v[98:99]
	v_lshlrev_b32_e32 v158, 16, v138
	v_mul_f32_e32 v127, 0x45800000, v97
	v_cndmask_b32_e64 v148, v97, v127, s[0:1]
	v_pk_mul_f32 v[152:153], v[148:149], v[152:153] op_sel_hi:[0,1]
	v_pk_mul_f32 v[142:143], v[148:149], v[142:143] op_sel_hi:[0,1]
	v_pk_fma_f32 v[92:93], v[28:29], v[152:153], v[92:93]
	v_pk_fma_f32 v[94:95], v[30:31], v[142:143], v[94:95]
	global_store_dwordx4 v[154:155], v[92:95], off nt
	v_and_b32_e32 v159, 0xffff0000, v138
	v_lshlrev_b32_e32 v138, 16, v139
	v_pk_mul_f32 v[92:93], v[148:149], v[156:157] op_sel_hi:[0,1]
	v_pk_fma_f32 v[80:81], v[24:25], v[92:93], v[80:81]
	v_pk_mul_f32 v[92:93], v[148:149], v[140:141] op_sel_hi:[0,1]
	v_and_b32_e32 v139, 0xffff0000, v139
	v_pk_fma_f32 v[82:83], v[26:27], v[92:93], v[82:83]
	global_store_dwordx4 v[150:151], v[80:83], off offset:1024 nt
	v_lshlrev_b32_e32 v160, 16, v132
	v_and_b32_e32 v161, 0xffff0000, v132
	v_pk_mul_f32 v[80:81], v[148:149], v[158:159] op_sel_hi:[0,1]
	v_pk_mul_f32 v[82:83], v[148:149], v[138:139] op_sel_hi:[0,1]
	v_pk_fma_f32 v[80:81], v[20:21], v[80:81], v[84:85]
	v_pk_fma_f32 v[82:83], v[22:23], v[82:83], v[86:87]
	v_lshlrev_b32_e32 v132, 16, v133
	v_and_b32_e32 v133, 0xffff0000, v133
	global_store_dwordx4 v[150:151], v[80:83], off offset:2048 nt
	v_lshlrev_b32_e32 v162, 16, v136
	v_and_b32_e32 v163, 0xffff0000, v136
	v_pk_mul_f32 v[80:81], v[148:149], v[160:161] op_sel_hi:[0,1]
	v_pk_fma_f32 v[64:65], v[16:17], v[80:81], v[64:65]
	v_pk_mul_f32 v[80:81], v[148:149], v[132:133] op_sel_hi:[0,1]
	v_lshlrev_b32_e32 v136, 16, v137
	v_and_b32_e32 v137, 0xffff0000, v137
	v_pk_fma_f32 v[66:67], v[18:19], v[80:81], v[66:67]
	global_store_dwordx4 v[150:151], v[64:67], off offset:3072 nt
	v_add_co_u32_e64 v80, s[0:1], s11, v150
	s_nop 0
	v_pk_mul_f32 v[64:65], v[148:149], v[162:163] op_sel_hi:[0,1]
	v_pk_mul_f32 v[66:67], v[148:149], v[136:137] op_sel_hi:[0,1]
	v_lshlrev_b32_e32 v164, 16, v134
	v_and_b32_e32 v165, 0xffff0000, v134
	v_lshlrev_b32_e32 v134, 16, v135
	v_and_b32_e32 v135, 0xffff0000, v135
	v_pk_fma_f32 v[64:65], v[12:13], v[64:65], v[88:89]
; DI float bflo(unsigned w) { return __uint_as_float(w << 16); }
; DI float bfhi(unsigned w) { return __uint_as_float(w & 0xffff0000u); }
; DI void phase_final(const Params& p) {
;     ...
; #pragma unroll
;         for (int r = 0; r < 2; ++r) {
;             const float rs = rsqrtf(wave_sum(sq[r]) * (1.f / DM) + EPS);
; #pragma unroll
;             for (int i = 0; i < 8; ++i) { const size_t off = (size_t)(row + r) * DM + i * 256 + lane * 4;
;                 const f32x4 ov = {xv[r][i][0] + bflo(yv[r][i][0]) * rs * w[i][0], xv[r][i][1] + bfhi(yv[r][i][0]) * rs * w[i][1],
;                                   xv[r][i][2] + bflo(yv[r][i][1]) * rs * w[i][2], xv[r][i][3] + bfhi(yv[r][i][1]) * rs * w[i][3]};
;                 __builtin_nontemporal_store(ov, (f32x4*)(p.out + off)); }
;         }
	v_pk_fma_f32 v[66:67], v[14:15], v[66:67], v[90:91]
	v_addc_co_u32_e64 v81, s[0:1], 0, v151, s[0:1]
	global_store_dwordx4 v[80:81], v[64:67], off nt
	v_lshlrev_b32_e32 v166, 16, v130
	v_and_b32_e32 v167, 0xffff0000, v130
	v_pk_mul_f32 v[64:65], v[148:149], v[164:165] op_sel_hi:[0,1]
	v_pk_mul_f32 v[66:67], v[148:149], v[134:135] op_sel_hi:[0,1]
	v_lshlrev_b32_e32 v130, 16, v131
	v_and_b32_e32 v131, 0xffff0000, v131
	v_pk_fma_f32 v[64:65], v[8:9], v[64:65], v[76:77]
	v_pk_fma_f32 v[66:67], v[10:11], v[66:67], v[78:79]
	global_store_dwordx4 v[80:81], v[64:67], off offset:1024 nt
	v_lshlrev_b32_e32 v168, 16, v128
	v_and_b32_e32 v169, 0xffff0000, v128
	v_pk_mul_f32 v[64:65], v[148:149], v[166:167] op_sel_hi:[0,1]
	v_pk_mul_f32 v[66:67], v[148:149], v[130:131] op_sel_hi:[0,1]
	v_pk_fma_f32 v[64:65], v[4:5], v[64:65], v[72:73]
	v_pk_fma_f32 v[66:67], v[6:7], v[66:67], v[74:75]
	global_store_dwordx4 v[80:81], v[64:67], off offset:2048 nt
	v_cmp_gt_f32_e64 s[0:1], s13, v126
	v_lshlrev_b32_e32 v128, 16, v129
	v_pk_mul_f32 v[64:65], v[148:149], v[168:169] op_sel_hi:[0,1]
	v_pk_fma_f32 v[60:61], v[0:1], v[64:65], v[60:61]
	v_mul_f32_e32 v64, 0x4b800000, v126
	v_cndmask_b32_e64 v64, v126, v64, s[0:1]
	v_rsq_f32_e32 v66, v64
	v_and_b32_e32 v129, 0xffff0000, v129
	v_pk_mul_f32 v[64:65], v[148:149], v[128:129] op_sel_hi:[0,1]
	v_pk_fma_f32 v[62:63], v[2:3], v[64:65], v[62:63]
	global_store_dwordx4 v[80:81], v[60:63], off offset:3072 nt
	v_add_u32_e32 v96, s12, v96
	s_nop 0
	v_mul_f32_e32 v60, 0x45800000, v66
	v_cndmask_b32_e64 v64, v66, v60, s[0:1]
	v_lshlrev_b32_e32 v60, 16, v124
	v_and_b32_e32 v61, 0xffff0000, v124
	v_lshlrev_b32_e32 v62, 16, v125
	v_and_b32_e32 v63, 0xffff0000, v125
	v_lshlrev_b64 v[66:67], 13, v[118:119]
	v_pk_mul_f32 v[60:61], v[64:65], v[60:61] op_sel_hi:[0,1]
	v_pk_mul_f32 v[62:63], v[64:65], v[62:63] op_sel_hi:[0,1]
	v_pk_fma_f32 v[60:61], v[28:29], v[60:61], v[68:69]
	v_pk_fma_f32 v[62:63], v[30:31], v[62:63], v[70:71]
	v_lshl_add_u64 v[68:69], v[104:105], 0, v[66:67]
	global_store_dwordx4 v[68:69], v[60:63], off nt
	s_nop 1
	v_lshlrev_b32_e32 v60, 16, v122
	v_and_b32_e32 v61, 0xffff0000, v122
	v_pk_mul_f32 v[60:61], v[64:65], v[60:61] op_sel_hi:[0,1]
	v_pk_fma_f32 v[56:57], v[24:25], v[60:61], v[56:57]
	v_lshlrev_b32_e32 v60, 16, v123
	v_and_b32_e32 v61, 0xffff0000, v123
	v_pk_mul_f32 v[60:61], v[64:65], v[60:61] op_sel_hi:[0,1]
	v_pk_fma_f32 v[58:59], v[26:27], v[60:61], v[58:59]
	v_lshl_add_u64 v[60:61], s[6:7], 0, v[66:67]
	v_lshl_add_u64 v[60:61], v[60:61], 0, v[98:99]
	global_store_dwordx4 v[60:61], v[56:59], off offset:1024 nt
	s_nop 1
	v_lshlrev_b32_e32 v56, 16, v120
	v_and_b32_e32 v57, 0xffff0000, v120
	v_pk_mul_f32 v[56:57], v[64:65], v[56:57] op_sel_hi:[0,1]
	v_pk_fma_f32 v[52:53], v[20:21], v[56:57], v[52:53]
	v_lshlrev_b32_e32 v56, 16, v121
	v_and_b32_e32 v57, 0xffff0000, v121
	v_pk_mul_f32 v[56:57], v[64:65], v[56:57] op_sel_hi:[0,1]
	v_pk_fma_f32 v[54:55], v[22:23], v[56:57], v[54:55]
	global_store_dwordx4 v[60:61], v[52:55], off offset:2048 nt
	s_nop 1
	v_lshlrev_b32_e32 v52, 16, v116
	v_and_b32_e32 v53, 0xffff0000, v116
	v_pk_mul_f32 v[52:53], v[64:65], v[52:53] op_sel_hi:[0,1]
	v_pk_fma_f32 v[48:49], v[16:17], v[52:53], v[48:49]
	v_lshlrev_b32_e32 v52, 16, v117
	v_and_b32_e32 v53, 0xffff0000, v117
	v_pk_mul_f32 v[52:53], v[64:65], v[52:53] op_sel_hi:[0,1]
	v_pk_fma_f32 v[50:51], v[18:19], v[52:53], v[50:51]
	global_store_dwordx4 v[60:61], v[48:51], off offset:3072 nt
	s_waitcnt vmcnt(19)
	s_nop 0
	v_lshlrev_b32_e32 v48, 16, v114
	v_and_b32_e32 v49, 0xffff0000, v114
	v_pk_mul_f32 v[48:49], v[64:65], v[48:49] op_sel_hi:[0,1]
	s_waitcnt vmcnt(18)
	v_pk_fma_f32 v[44:45], v[12:13], v[48:49], v[44:45]
	v_lshlrev_b32_e32 v48, 16, v115
	v_and_b32_e32 v49, 0xffff0000, v115
	v_pk_mul_f32 v[48:49], v[64:65], v[48:49] op_sel_hi:[0,1]
	v_pk_fma_f32 v[46:47], v[14:15], v[48:49], v[46:47]
	v_add_co_u32_e64 v48, s[0:1], s11, v60
	s_nop 1
	v_addc_co_u32_e64 v49, s[0:1], 0, v61, s[0:1]
	global_store_dwordx4 v[48:49], v[44:47], off nt
	v_cmp_lt_i32_e64 s[0:1], s14, v96
	s_or_b64 s[8:9], s[0:1], s[8:9]
	s_waitcnt vmcnt(18)
	v_lshlrev_b32_e32 v44, 16, v112
	v_and_b32_e32 v45, 0xffff0000, v112
	v_pk_mul_f32 v[44:45], v[64:65], v[44:45] op_sel_hi:[0,1]
	s_waitcnt vmcnt(17)
	v_pk_fma_f32 v[40:41], v[8:9], v[44:45], v[40:41]
	v_lshlrev_b32_e32 v44, 16, v113
	v_and_b32_e32 v45, 0xffff0000, v113
	v_pk_mul_f32 v[44:45], v[64:65], v[44:45] op_sel_hi:[0,1]
	v_pk_fma_f32 v[42:43], v[10:11], v[44:45], v[42:43]
	global_store_dwordx4 v[48:49], v[40:43], off offset:1024 nt
	s_waitcnt vmcnt(17)
	s_nop 0
	v_lshlrev_b32_e32 v40, 16, v110
	v_and_b32_e32 v41, 0xffff0000, v110
	v_pk_mul_f32 v[40:41], v[64:65], v[40:41] op_sel_hi:[0,1]
	s_waitcnt vmcnt(16)
	v_pk_fma_f32 v[36:37], v[4:5], v[40:41], v[36:37]
	v_lshlrev_b32_e32 v40, 16, v111
	v_and_b32_e32 v41, 0xffff0000, v111
	v_pk_mul_f32 v[40:41], v[64:65], v[40:41] op_sel_hi:[0,1]
	v_pk_fma_f32 v[38:39], v[6:7], v[40:41], v[38:39]
	global_store_dwordx4 v[48:49], v[36:39], off offset:2048 nt
	s_waitcnt vmcnt(16)
	s_nop 0
	v_lshlrev_b32_e32 v36, 16, v108
	v_and_b32_e32 v37, 0xffff0000, v108
	v_pk_mul_f32 v[36:37], v[64:65], v[36:37] op_sel_hi:[0,1]
	s_waitcnt vmcnt(15)
	v_pk_fma_f32 v[32:33], v[0:1], v[36:37], v[32:33]
	v_lshlrev_b32_e32 v36, 16, v109
	v_and_b32_e32 v37, 0xffff0000, v109
	v_pk_mul_f32 v[36:37], v[64:65], v[36:37] op_sel_hi:[0,1]
	v_pk_fma_f32 v[34:35], v[2:3], v[36:37], v[34:35]
	global_store_dwordx4 v[48:49], v[32:35], off offset:3072 nt
	s_andn2_b64 exec, exec, s[8:9]
	s_cbranch_execz .LBB0_603

; DI void phase_final(const Params& p) {
;     ...
;     for (int row = (blockIdx.x * 8 + wid) * 2; row < S; row += gridDim.x * 16) {
;         f32x4 xv[2][8]; u32x2 yv[2][8]; float sq[2];
; #pragma unroll
;         for (int r = 0; r < 2; ++r) {
;             sq[r] = lane < 32 ? ssq[(size_t)(row + r) * 32 + lane] : 0.f;
; #pragma unroll
;             for (int i = 0; i < 8; ++i) { const size_t off = (size_t)(row + r) * DM + i * 256 + lane * 4; xv[r][i] = __builtin_nontemporal_load((const f32x4*)(x + off)); yv[r][i] = __builtin_nontemporal_load((const u32x2*)(o2 + off)); }
;         }
.LBB0_601:
	s_or_b64 exec, exec, s[0:1]
	v_lshlrev_b64 v[32:33], 11, v[96:97]
	v_or_b32_e32 v32, v32, v100
	v_lshlrev_b64 v[36:37], 1, v[32:33]
	v_lshl_add_u64 v[34:35], v[32:33], 2, s[2:3]
	v_lshl_add_u64 v[38:39], s[4:5], 0, v[36:37]
	v_or_b32_e32 v40, 0x200, v36
	v_or_b32_e32 v42, 0x400, v36
	v_or_b32_e32 v36, 0x600, v36
	global_load_dwordx4 v[92:95], v[34:35], off
	global_load_dwordx4 v[80:83], v[34:35], off offset:1024
	v_mov_b32_e32 v41, v37
	v_mov_b32_e32 v43, v37
	global_load_dwordx4 v[84:87], v[34:35], off offset:2048
	global_load_dwordx4 v[64:67], v[34:35], off offset:3072
	v_lshl_add_u64 v[34:35], s[4:5], 0, v[36:37]
	v_lshl_add_u64 v[40:41], s[4:5], 0, v[40:41]
	v_lshl_add_u64 v[42:43], s[4:5], 0, v[42:43]
	global_load_dwordx2 v[142:143], v[38:39], off
	global_load_dwordx2 v[140:141], v[40:41], off
	global_load_dwordx2 v[138:139], v[42:43], off
	global_load_dwordx2 v[132:133], v[34:35], off
	v_or_b32_e32 v34, 0x400, v32
	v_mov_b32_e32 v35, v33
	v_lshl_add_u64 v[36:37], v[34:35], 2, s[2:3]
	v_lshl_add_u64 v[34:35], v[34:35], 1, s[4:5]
	global_load_dwordx2 v[136:137], v[34:35], off
	v_or_b32_e32 v34, 0x500, v32
	v_mov_b32_e32 v35, v33
	global_load_dwordx4 v[88:91], v[36:37], off
	v_lshl_add_u64 v[36:37], v[34:35], 2, s[2:3]
	v_lshl_add_u64 v[34:35], v[34:35], 1, s[4:5]
	global_load_dwordx2 v[134:135], v[34:35], off
	v_or_b32_e32 v34, 0x600, v32
	v_mov_b32_e32 v35, v33
	global_load_dwordx4 v[76:79], v[36:37], off
	v_lshl_add_u64 v[36:37], v[34:35], 2, s[2:3]
	v_lshl_add_u64 v[34:35], v[34:35], 1, s[4:5]
	v_or_b32_e32 v32, 0x700, v32
	global_load_dwordx2 v[130:131], v[34:35], off
	v_lshl_add_u64 v[34:35], v[32:33], 2, s[2:3]
	v_lshl_add_u64 v[32:33], v[32:33], 1, s[4:5]
	global_load_dwordx4 v[72:75], v[36:37], off
	global_load_dwordx4 v[60:63], v[34:35], off
	global_load_dwordx2 v[128:129], v[32:33], off
	v_add_u32_e32 v118, 1, v96
	v_ashrrev_i32_e32 v119, 31, v118
	v_mov_b32_e32 v126, 0
	s_and_saveexec_b64 s[0:1], vcc
	s_cbranch_execz .LBB0_598
	v_lshlrev_b64 v[32:33], 7, v[118:119]
	v_lshl_add_u64 v[32:33], v[102:103], 0, v[32:33]
	global_load_dword v126, v[32:33], off
	s_branch .LBB0_598
